# grid barrier: followers wait on the cross-XCD generation word directly (no per-XCD release hop), leader and follower L1 invalidates overlapped with the arrival atomics, also in the prologue barrier
# speedup vs baseline: 1.0032x; 1.0032x over previous
.LBB0_89:
	s_or_b64 exec, exec, s[10:11]
	v_cvt_f32_u32_e32 v4, v2
	s_waitcnt vmcnt(0)
	v_readfirstlane_b32 s2, v3
	v_sub_u32_e32 v3, 0, v2
	v_rcp_iflag_f32_e32 v4, v4
	v_add_u32_e32 v5, s2, v1
	v_mul_f32_e32 v4, 0x4f7ffffe, v4
	v_cvt_u32_f32_e32 v4, v4
	v_mul_lo_u32 v1, v3, v4
	v_mul_hi_u32 v1, v4, v1
	v_add_u32_e32 v1, v4, v1
	v_mul_hi_u32 v1, v5, v1
	v_mul_lo_u32 v3, v1, v2
	v_sub_u32_e32 v3, v5, v3
	v_add_u32_e32 v4, 1, v1
	v_cmp_ge_u32_e32 vcc, v3, v2
	s_nop 1
	v_cndmask_b32_e32 v1, v1, v4, vcc
	v_sub_u32_e32 v4, v3, v2
	v_cndmask_b32_e32 v3, v3, v4, vcc
	v_add_u32_e32 v4, 1, v1
	v_cmp_ge_u32_e32 vcc, v3, v2
	v_add_u32_e32 v3, 1, v5
	s_nop 0
	v_cndmask_b32_e32 v1, v1, v4, vcc
	v_mul_lo_u32 v4, v2, v1
	v_add_u32_e32 v2, v4, v2
	v_cmp_ne_u32_e32 vcc, v3, v2
	s_and_saveexec_b64 s[8:9], vcc
	s_xor_b64 s[8:9], exec, s[8:9]
	s_cbranch_execz .LBB0_103
	s_waitcnt lgkmcnt(0)
	buffer_inv sc1
	v_mov_b32_e32 v0, 0x2000
	global_load_dword v0, v0, s[4:5] offset:1024 sc1
	s_add_u32 s14, s4, 0x2400
	s_addc_u32 s15, s5, 0
	s_waitcnt vmcnt(0)
	v_cmp_eq_u32_e32 vcc, v0, v1
	s_and_saveexec_b64 s[10:11], vcc
	s_cbranch_execz .LBB0_102
	v_readlane_b32 s16, v247, 0
	v_readlane_b32 s18, v247, 2
	v_readlane_b32 s17, v247, 1
	v_readlane_b32 s19, v247, 3
	s_add_u32 s12, s18, 0x80200
	s_addc_u32 s13, s19, 0
	s_mov_b32 s2, 1
	s_mov_b64 s[16:17], 0
	v_mov_b32_e32 v0, 0
	s_branch .LBB0_93

.LBB0_102:
	s_or_b64 exec, exec, s[10:11]
	s_waitcnt vmcnt(0)
.LBB0_103:
	s_andn2_saveexec_b64 s[8:9], s[8:9]
	s_cbranch_execz .LBB0_123
	s_mov_b64 s[8:9], exec
	buffer_wbl2 sc1
	s_waitcnt lgkmcnt(0)
	s_waitcnt vmcnt(0)
	v_mbcnt_lo_u32_b32 v1, s8, 0
	v_mbcnt_hi_u32_b32 v1, s9, v1
	v_cmp_eq_u32_e32 vcc, 0, v1
	s_and_saveexec_b64 s[10:11], vcc
	s_cbranch_execz .LBB0_106
	s_bcnt1_i32_b64 s2, s[8:9]
	v_readlane_b32 s12, v247, 0
	v_mov_b32_e32 v2, 0x83000
	v_mov_b32_e32 v3, s2
	v_readlane_b32 s14, v247, 2
	v_readlane_b32 s15, v247, 3
	v_readlane_b32 s13, v247, 1
	s_nop 3
	global_atomic_add v2, v2, v3, s[14:15] offset:1024 sc0

.LBB0_651:
	s_or_b64 exec, exec, s[6:7]
	v_cvt_f32_u32_e32 v4, v2
	s_waitcnt vmcnt(0)
	v_readfirstlane_b32 s6, v3
	v_sub_u32_e32 v3, 0, v2
	v_rcp_iflag_f32_e32 v4, v4
	v_add_u32_e32 v5, s6, v1
	v_mul_f32_e32 v4, 0x4f7ffffe, v4
	v_cvt_u32_f32_e32 v4, v4
	v_mul_lo_u32 v1, v3, v4
	v_mul_hi_u32 v1, v4, v1
	v_add_u32_e32 v1, v4, v1
	v_mul_hi_u32 v1, v5, v1
	v_mul_lo_u32 v3, v1, v2
	v_sub_u32_e32 v3, v5, v3
	v_add_u32_e32 v4, 1, v1
	v_cmp_ge_u32_e32 vcc, v3, v2
	s_nop 1
	v_cndmask_b32_e32 v1, v1, v4, vcc
	v_sub_u32_e32 v4, v3, v2
	v_cndmask_b32_e32 v3, v3, v4, vcc
	v_add_u32_e32 v4, 1, v1
	v_cmp_ge_u32_e32 vcc, v3, v2
	v_add_u32_e32 v3, 1, v5
	s_nop 0
	v_cndmask_b32_e32 v1, v1, v4, vcc
	v_mul_lo_u32 v4, v2, v1
	v_add_u32_e32 v2, v4, v2
	v_cmp_ne_u32_e32 vcc, v3, v2
	s_and_saveexec_b64 s[6:7], vcc
	s_xor_b64 s[6:7], exec, s[6:7]
	s_cbranch_execz .LBB0_665
	v_readlane_b32 s8, v245, 13
	v_readlane_b32 s9, v245, 14
	s_waitcnt lgkmcnt(0)
	buffer_inv sc1
	s_nop 3
	global_load_dword v0, v137, s[8:9] sc1
	s_waitcnt vmcnt(0)
	v_cmp_eq_u32_e32 vcc, v0, v1
	s_and_saveexec_b64 s[8:9], vcc
	s_cbranch_execz .LBB0_664
	s_mov_b32 s20, 1
	s_mov_b64 s[10:11], 0
	s_branch .LBB0_655

.LBB0_659:
	v_readlane_b32 s14, v245, 13
	v_readlane_b32 s15, v245, 14
	s_add_i32 s20, s20, 1
	s_mov_b64 s[16:17], -1
	s_nop 2
	global_load_dword v0, v137, s[14:15] sc1
	s_waitcnt vmcnt(0)
	v_cmp_ne_u32_e32 vcc, v0, v1
	s_orn2_b64 s[14:15], vcc, exec
	s_branch .LBB0_654
